# out-proj L0 post-loop rewritten: last k-tile with pipelined LDS fragment reads, residual epilogue (out = x + acc) with x loads batched 8 rows ahead and counted vmcnt instead of 128 serialized load-wai
# speedup vs baseline: 1.0438x; 1.0320x over previous
.LBB0_620:
	s_add_i32 s24, s4, 1
	s_and_b32 s5, s24, 56
	s_cmp_eq_u32 s5, 8
	s_cselect_b32 s5, s13, 0x3000000
	s_add_u32 s5, s86, s5
	s_addc_u32 s25, s87, 0
	s_cmp_lt_u32 s4, 7
	s_cselect_b32 s4, s8, s25
	s_cselect_b32 s5, s7, s5
	s_and_b32 s25, s22, 0x1c0
	s_add_u32 s5, s5, s21
	s_addc_u32 s26, s4, 0
	s_lshl_b32 s4, s25, 1
	s_add_u32 s4, s5, s4
	s_addc_u32 s5, s26, 0
	s_and_b32 s25, s23, 0x10000
	s_add_i32 s25, s25, 16
	v_add_u32_e32 v141, s25, v139
	v_add3_u32 v142, v141, v166, v164
	v_add3_u32 v141, v141, v165, v164
	ds_read_b128 v[146:149], v142
	ds_read_b128 v[150:153], v141 offset:32768
	ds_read_b128 v[154:157], v142 offset:4096
	ds_read_b128 v[158:161], v141 offset:36864
	s_waitcnt lgkmcnt(2)
	v_mfma_f32_32x32x16_bf16 v[112:127], v[146:149], v[150:153], v[112:127]
	v_add_u32_e32 v141, s25, v138
	s_add_i32 s23, s23, 0x10000
	s_waitcnt lgkmcnt(0)
	v_mfma_f32_32x32x16_bf16 v[96:111], v[146:149], v[158:161], v[96:111]
	v_mfma_f32_32x32x16_bf16 v[80:95], v[154:157], v[150:153], v[80:95]
	v_mfma_f32_32x32x16_bf16 v[64:79], v[154:157], v[158:161], v[64:79]
	ds_read_b128 v[146:149], v142 offset:8192
	ds_read_b128 v[154:157], v142 offset:12288
	v_add3_u32 v142, v141, v166, v164
	v_add3_u32 v141, v141, v165, v164
	s_waitcnt lgkmcnt(1)
	v_mfma_f32_32x32x16_bf16 v[48:63], v[146:149], v[150:153], v[48:63]
	v_mfma_f32_32x32x16_bf16 v[32:47], v[146:149], v[158:161], v[32:47]
	s_waitcnt lgkmcnt(0)
	v_mfma_f32_32x32x16_bf16 v[16:31], v[154:157], v[150:153], v[16:31]
	v_mfma_f32_32x32x16_bf16 v[0:15], v[154:157], v[158:161], v[0:15]
	ds_read_b128 v[146:149], v142
	ds_read_b128 v[150:153], v141 offset:32768
	ds_read_b128 v[154:157], v142 offset:4096
	ds_read_b128 v[158:161], v141 offset:36864
	v_add_u32_e32 v141, s25, v144
	s_waitcnt lgkmcnt(2)
	v_mfma_f32_32x32x16_bf16 v[112:127], v[146:149], v[150:153], v[112:127]
	s_waitcnt lgkmcnt(0)
	v_mfma_f32_32x32x16_bf16 v[96:111], v[146:149], v[158:161], v[96:111]
	v_mfma_f32_32x32x16_bf16 v[80:95], v[154:157], v[150:153], v[80:95]
	v_mfma_f32_32x32x16_bf16 v[64:79], v[154:157], v[158:161], v[64:79]
	ds_read_b128 v[146:149], v142 offset:8192
	ds_read_b128 v[154:157], v142 offset:12288
	v_add3_u32 v142, v141, v166, v164
	v_add3_u32 v141, v141, v165, v164
	s_waitcnt lgkmcnt(1)
	v_mfma_f32_32x32x16_bf16 v[48:63], v[146:149], v[150:153], v[48:63]
	v_mfma_f32_32x32x16_bf16 v[32:47], v[146:149], v[158:161], v[32:47]
	s_waitcnt lgkmcnt(0)
	v_mfma_f32_32x32x16_bf16 v[16:31], v[154:157], v[150:153], v[16:31]
	v_mfma_f32_32x32x16_bf16 v[0:15], v[154:157], v[158:161], v[0:15]
	ds_read_b128 v[146:149], v142
	ds_read_b128 v[150:153], v141 offset:32768
	ds_read_b128 v[154:157], v142 offset:4096
	ds_read_b128 v[158:161], v141 offset:36864
	v_add_u32_e32 v141, s25, v167
	v_add3_u32 v145, v141, v166, v164
	v_add3_u32 v141, v141, v165, v164
	s_waitcnt lgkmcnt(2)
	v_mfma_f32_32x32x16_bf16 v[112:127], v[146:149], v[150:153], v[112:127]
	s_waitcnt lgkmcnt(0)
	v_mfma_f32_32x32x16_bf16 v[96:111], v[146:149], v[158:161], v[96:111]
	v_mfma_f32_32x32x16_bf16 v[80:95], v[154:157], v[150:153], v[80:95]
	v_mfma_f32_32x32x16_bf16 v[64:79], v[154:157], v[158:161], v[64:79]
	ds_read_b128 v[146:149], v142 offset:8192
	ds_read_b128 v[154:157], v142 offset:12288
	v_lshl_add_u64 v[142:143], v[136:137], 0, s[0:1]
	v_add_co_u32_e32 v162, vcc, s14, v142
	s_nop 1
	v_addc_co_u32_e32 v163, vcc, 0, v143, vcc
	v_add_co_u32_e32 v168, vcc, s15, v142
	s_waitcnt lgkmcnt(1)
	v_mfma_f32_32x32x16_bf16 v[48:63], v[146:149], v[150:153], v[48:63]
	v_addc_co_u32_e32 v169, vcc, 0, v143, vcc
	v_add_co_u32_e32 v172, vcc, s16, v142
	s_nop 1
	v_addc_co_u32_e32 v173, vcc, 0, v143, vcc
	v_mfma_f32_32x32x16_bf16 v[32:47], v[146:149], v[158:161], v[32:47]
	v_add_co_u32_e32 v142, vcc, s17, v142
	s_nop 1
	v_addc_co_u32_e32 v143, vcc, 0, v143, vcc
	s_waitcnt lgkmcnt(0)
	v_mfma_f32_32x32x16_bf16 v[16:31], v[154:157], v[150:153], v[16:31]
	v_mfma_f32_32x32x16_bf16 v[0:15], v[154:157], v[158:161], v[0:15]
	ds_read_b128 v[146:149], v145
	ds_read_b128 v[150:153], v141 offset:32768
	ds_read_b128 v[154:157], v145 offset:4096
	ds_read_b128 v[158:161], v141 offset:36864
	s_waitcnt lgkmcnt(2)
	v_mfma_f32_32x32x16_bf16 v[112:127], v[146:149], v[150:153], v[112:127]
	s_waitcnt lgkmcnt(0)
	v_mfma_f32_32x32x16_bf16 v[96:111], v[146:149], v[158:161], v[96:111]
	global_load_dwordx4 v[146:149], v[162:163], off offset:128
	s_nop 0
	global_load_dwordx4 v[168:171], v[168:169], off offset:128
	s_nop 0
	global_load_dwordx4 v[172:175], v[172:173], off offset:128
	s_nop 0
	global_load_dwordx4 v[176:179], v[142:143], off offset:128
	v_lshl_add_u64 v[142:143], s[4:5], 0, v[208:209]
	v_lshl_add_u64 v[162:163], v[142:143], 0, v[128:129]
	v_lshl_add_u64 v[188:189], v[142:143], 0, v[130:131]
	v_lshl_add_u64 v[192:193], v[142:143], 0, v[132:133]
	v_lshl_add_u64 v[142:143], v[142:143], 0, v[134:135]
	s_and_b32 s5, s23, 0x10000
	v_mfma_f32_32x32x16_bf16 v[80:95], v[154:157], v[150:153], v[80:95]
	s_add_u32 s0, s0, 0x80
	s_addc_u32 s1, s1, 0
	s_add_i32 s22, s22, 64
	s_mov_b32 s4, s24
	v_add_u32_e32 v141, s5, v140
	s_cmpk_lg_i32 s0, 0xb80
	v_mfma_f32_32x32x16_bf16 v[64:79], v[154:157], v[158:161], v[64:79]
	ds_read_b128 v[154:157], v145 offset:8192
	ds_read_b128 v[180:183], v145 offset:12288
	global_load_dwordx4 v[184:187], v[162:163], off
	s_nop 0
	global_load_dwordx4 v[188:191], v[188:189], off
	s_nop 0
	global_load_dwordx4 v[192:195], v[192:193], off
	s_waitcnt lgkmcnt(1)
	v_mfma_f32_32x32x16_bf16 v[48:63], v[154:157], v[150:153], v[48:63]
	v_mfma_f32_32x32x16_bf16 v[32:47], v[154:157], v[158:161], v[32:47]
	global_load_dwordx4 v[154:157], v[142:143], off
	s_waitcnt vmcnt(7)
	ds_write_b128 v141, v[146:149] offset:32768
	s_waitcnt vmcnt(6)
	ds_write_b128 v141, v[168:171] offset:40960
	s_waitcnt vmcnt(5)
	ds_write_b128 v141, v[172:175] offset:49152
	s_waitcnt vmcnt(4)
	ds_write_b128 v141, v[176:179] offset:57344
	s_waitcnt vmcnt(3)
	ds_write_b128 v141, v[184:187]
	s_waitcnt vmcnt(2)
	ds_write_b128 v141, v[188:191] offset:8192
	s_waitcnt vmcnt(1)
	ds_write_b128 v141, v[192:195] offset:16384
	s_waitcnt vmcnt(0)
	ds_write_b128 v141, v[154:157] offset:24576
	s_waitcnt lgkmcnt(8)
	v_mfma_f32_32x32x16_bf16 v[16:31], v[180:183], v[150:153], v[16:31]
	s_waitcnt lgkmcnt(0)
	s_barrier
	v_mfma_f32_32x32x16_bf16 v[0:15], v[180:183], v[158:161], v[0:15]
	s_cbranch_scc1 .LBB0_620
	s_mov_b32 s0, 0x10000
	v_add3_u32 v226, v166, v164, 16
	v_add3_u32 v227, v165, v164, 16
	v_add3_u32 v229, v139, v227, s0
	v_add3_u32 v228, v139, v226, s0
	ds_read_b128 v[192:195], v229 offset:32768
	ds_read_b128 v[200:203], v229 offset:36864
	ds_read_b128 v[172:175], v228
	ds_read_b128 v[176:179], v228 offset:4096
	ds_read_b128 v[180:183], v228 offset:8192
	ds_read_b128 v[184:187], v228 offset:12288
	v_add3_u32 v228, v138, v226, s0
	ds_read_b128 v[188:191], v228
	v_add3_u32 v229, v138, v227, s0
	ds_read_b128 v[204:207], v229 offset:32768
	ds_read_b128 v[222:225], v229 offset:36864
	s_waitcnt lgkmcnt(6)
	v_mfma_f32_32x32x16_bf16 v[112:127], v[172:175], v[192:195], v[112:127]
	v_mfma_f32_32x32x16_bf16 v[96:111], v[172:175], v[200:203], v[96:111]
	ds_read_b128 v[172:175], v228 offset:4096
	s_waitcnt lgkmcnt(6)
	v_mfma_f32_32x32x16_bf16 v[80:95], v[176:179], v[192:195], v[80:95]
	v_mfma_f32_32x32x16_bf16 v[64:79], v[176:179], v[200:203], v[64:79]
	ds_read_b128 v[176:179], v228 offset:8192
	s_waitcnt lgkmcnt(6)
	v_mfma_f32_32x32x16_bf16 v[48:63], v[180:183], v[192:195], v[48:63]
	v_mfma_f32_32x32x16_bf16 v[32:47], v[180:183], v[200:203], v[32:47]
	ds_read_b128 v[180:183], v228 offset:12288
	s_waitcnt lgkmcnt(6)
	v_mfma_f32_32x32x16_bf16 v[16:31], v[184:187], v[192:195], v[16:31]
	v_mfma_f32_32x32x16_bf16 v[0:15], v[184:187], v[200:203], v[0:15]
	v_add3_u32 v228, v144, v226, s0
	ds_read_b128 v[184:187], v228
	v_add3_u32 v229, v144, v227, s0
	ds_read_b128 v[192:195], v229 offset:32768
	ds_read_b128 v[200:203], v229 offset:36864
	s_waitcnt lgkmcnt(6)
	v_mfma_f32_32x32x16_bf16 v[112:127], v[188:191], v[204:207], v[112:127]
	v_mfma_f32_32x32x16_bf16 v[96:111], v[188:191], v[222:225], v[96:111]
	ds_read_b128 v[188:191], v228 offset:4096
	s_waitcnt lgkmcnt(6)
	v_mfma_f32_32x32x16_bf16 v[80:95], v[172:175], v[204:207], v[80:95]
	v_mfma_f32_32x32x16_bf16 v[64:79], v[172:175], v[222:225], v[64:79]
	ds_read_b128 v[172:175], v228 offset:8192
	s_waitcnt lgkmcnt(6)
	v_mfma_f32_32x32x16_bf16 v[48:63], v[176:179], v[204:207], v[48:63]
	v_mfma_f32_32x32x16_bf16 v[32:47], v[176:179], v[222:225], v[32:47]
	ds_read_b128 v[176:179], v228 offset:12288
	s_waitcnt lgkmcnt(6)
	v_mfma_f32_32x32x16_bf16 v[16:31], v[180:183], v[204:207], v[16:31]
	v_mfma_f32_32x32x16_bf16 v[0:15], v[180:183], v[222:225], v[0:15]
	v_add3_u32 v228, v167, v226, s0
	ds_read_b128 v[180:183], v228
	v_add3_u32 v229, v167, v227, s0
	ds_read_b128 v[204:207], v229 offset:32768
	ds_read_b128 v[222:225], v229 offset:36864
	s_waitcnt lgkmcnt(6)
	v_mfma_f32_32x32x16_bf16 v[112:127], v[184:187], v[192:195], v[112:127]
	v_mfma_f32_32x32x16_bf16 v[96:111], v[184:187], v[200:203], v[96:111]
	ds_read_b128 v[184:187], v228 offset:4096
	s_waitcnt lgkmcnt(6)
	v_mfma_f32_32x32x16_bf16 v[80:95], v[188:191], v[192:195], v[80:95]
	v_mfma_f32_32x32x16_bf16 v[64:79], v[188:191], v[200:203], v[64:79]
	ds_read_b128 v[188:191], v228 offset:8192
	s_waitcnt lgkmcnt(6)
	v_mfma_f32_32x32x16_bf16 v[48:63], v[172:175], v[192:195], v[48:63]
	v_mfma_f32_32x32x16_bf16 v[32:47], v[172:175], v[200:203], v[32:47]
	ds_read_b128 v[172:175], v228 offset:12288
	s_waitcnt lgkmcnt(6)
	v_mfma_f32_32x32x16_bf16 v[16:31], v[176:179], v[192:195], v[16:31]
	v_mfma_f32_32x32x16_bf16 v[0:15], v[176:179], v[200:203], v[0:15]
	s_waitcnt lgkmcnt(3)
	v_mfma_f32_32x32x16_bf16 v[112:127], v[180:183], v[204:207], v[112:127]
	v_mfma_f32_32x32x16_bf16 v[96:111], v[180:183], v[222:225], v[96:111]
	s_waitcnt lgkmcnt(2)
	v_mfma_f32_32x32x16_bf16 v[80:95], v[184:187], v[204:207], v[80:95]
	v_mfma_f32_32x32x16_bf16 v[64:79], v[184:187], v[222:225], v[64:79]
	s_waitcnt lgkmcnt(1)
	v_mfma_f32_32x32x16_bf16 v[48:63], v[188:191], v[204:207], v[48:63]
	v_mfma_f32_32x32x16_bf16 v[32:47], v[188:191], v[222:225], v[32:47]
	s_waitcnt lgkmcnt(0)
	v_mfma_f32_32x32x16_bf16 v[16:31], v[172:175], v[204:207], v[16:31]
	v_mfma_f32_32x32x16_bf16 v[0:15], v[172:175], v[222:225], v[0:15]
	s_waitcnt lgkmcnt(0)
	s_barrier
	v_readlane_b32 s36, v252, 6
	v_readlane_b32 s37, v252, 7
	v_readlane_b32 s38, v252, 8
	v_readlane_b32 s39, v252, 9
	v_readlane_b32 s40, v252, 10
	v_readlane_b32 s41, v252, 11
	v_readlane_b32 s42, v252, 12
	v_readlane_b32 s43, v252, 13
	v_readlane_b32 s44, v252, 14
	v_readlane_b32 s45, v252, 15
	v_readlane_b32 s46, v252, 16
	v_readlane_b32 s47, v252, 17
	v_readlane_b32 s48, v252, 18
	v_readlane_b32 s49, v252, 19
	v_readlane_b32 s50, v252, 20
	v_readlane_b32 s51, v252, 21
	s_add_i32 s2, s2, s92
	s_add_i32 s9, s9, s10
	v_lshl_add_u32 v211, v211, 7, s19
	v_lshl_or_b32 v212, v212, 2, v211
	v_lshl_or_b32 v208, v213, 6, s20
	v_or_b32_e32 v210, v208, v210
	v_lshl_add_u32 v128, v212, 10, v210
	v_lshlrev_b32_e32 v128, 2, v128
	global_load_dword v172, v128, s[36:37]
	global_load_dword v173, v128, s[36:37] offset:128
	v_add_u32_e32 v129, 0x1000, v128
	global_load_dword v174, v129, s[36:37]
	global_load_dword v175, v129, s[36:37] offset:128
	v_add_u32_e32 v130, 0x1000, v129
	global_load_dword v176, v130, s[36:37]
	global_load_dword v177, v130, s[36:37] offset:128
	v_add_u32_e32 v131, 0x1000, v130
	global_load_dword v178, v131, s[36:37]
	global_load_dword v179, v131, s[36:37] offset:128
	v_add_u32_e32 v132, 0x5000, v131
	global_load_dword v180, v132, s[36:37]
	global_load_dword v181, v132, s[36:37] offset:128
	v_add_u32_e32 v133, 0x1000, v132
	global_load_dword v182, v133, s[36:37]
	global_load_dword v183, v133, s[36:37] offset:128
	v_add_u32_e32 v134, 0x1000, v133
	global_load_dword v184, v134, s[36:37]
	global_load_dword v185, v134, s[36:37] offset:128
	v_add_u32_e32 v135, 0x1000, v134
	global_load_dword v186, v135, s[36:37]
	global_load_dword v187, v135, s[36:37] offset:128
	v_add_u32_e32 v136, 0x5000, v135
	global_load_dword v188, v136, s[36:37]
	global_load_dword v189, v136, s[36:37] offset:128
	v_add_u32_e32 v137, 0x1000, v136
	global_load_dword v190, v137, s[36:37]
	global_load_dword v191, v137, s[36:37] offset:128
	v_add_u32_e32 v138, 0x1000, v137
	global_load_dword v192, v138, s[36:37]
	global_load_dword v193, v138, s[36:37] offset:128
	v_add_u32_e32 v139, 0x1000, v138
	global_load_dword v194, v139, s[36:37]
	global_load_dword v195, v139, s[36:37] offset:128
	v_add_u32_e32 v140, 0x5000, v139
	global_load_dword v196, v140, s[36:37]
	global_load_dword v197, v140, s[36:37] offset:128
	v_add_u32_e32 v141, 0x1000, v140
	global_load_dword v198, v141, s[36:37]
	global_load_dword v199, v141, s[36:37] offset:128
	v_add_u32_e32 v142, 0x1000, v141
	global_load_dword v200, v142, s[36:37]
	global_load_dword v201, v142, s[36:37] offset:128
	v_add_u32_e32 v143, 0x1000, v142
	global_load_dword v202, v143, s[36:37]
	global_load_dword v203, v143, s[36:37] offset:128
	s_waitcnt vmcnt(16)
	v_add_f32_e32 v172, v112, v172
	v_add_f32_e32 v173, v96, v173
	global_store_dword v128, v172, s[84:85]
	global_store_dword v128, v173, s[84:85] offset:128
	v_add_f32_e32 v174, v113, v174
	v_add_f32_e32 v175, v97, v175
	global_store_dword v129, v174, s[84:85]
	global_store_dword v129, v175, s[84:85] offset:128
	v_add_f32_e32 v176, v114, v176
	v_add_f32_e32 v177, v98, v177
	global_store_dword v130, v176, s[84:85]
	global_store_dword v130, v177, s[84:85] offset:128
	v_add_f32_e32 v178, v115, v178
	v_add_f32_e32 v179, v99, v179
	global_store_dword v131, v178, s[84:85]
	global_store_dword v131, v179, s[84:85] offset:128
	v_add_f32_e32 v180, v116, v180
	v_add_f32_e32 v181, v100, v181
	global_store_dword v132, v180, s[84:85]
	global_store_dword v132, v181, s[84:85] offset:128
	v_add_f32_e32 v182, v117, v182
	v_add_f32_e32 v183, v101, v183
	global_store_dword v133, v182, s[84:85]
	global_store_dword v133, v183, s[84:85] offset:128
	v_add_f32_e32 v184, v118, v184
	v_add_f32_e32 v185, v102, v185
	global_store_dword v134, v184, s[84:85]
	global_store_dword v134, v185, s[84:85] offset:128
	v_add_f32_e32 v186, v119, v186
	v_add_f32_e32 v187, v103, v187
	global_store_dword v135, v186, s[84:85]
	global_store_dword v135, v187, s[84:85] offset:128
	v_add_u32_e32 v128, 0x5000, v143
	global_load_dword v172, v128, s[36:37]
	global_load_dword v173, v128, s[36:37] offset:128
	v_add_u32_e32 v129, 0x1000, v128
	global_load_dword v174, v129, s[36:37]
	global_load_dword v175, v129, s[36:37] offset:128
	v_add_u32_e32 v130, 0x1000, v129
	global_load_dword v176, v130, s[36:37]
	global_load_dword v177, v130, s[36:37] offset:128
	v_add_u32_e32 v131, 0x1000, v130
	global_load_dword v178, v131, s[36:37]
	global_load_dword v179, v131, s[36:37] offset:128
	v_add_u32_e32 v132, 0x5000, v131
	global_load_dword v180, v132, s[36:37]
	global_load_dword v181, v132, s[36:37] offset:128
	v_add_u32_e32 v133, 0x1000, v132
	global_load_dword v182, v133, s[36:37]
	global_load_dword v183, v133, s[36:37] offset:128
	v_add_u32_e32 v134, 0x1000, v133
	global_load_dword v184, v134, s[36:37]
	global_load_dword v185, v134, s[36:37] offset:128
	v_add_u32_e32 v135, 0x1000, v134
	global_load_dword v186, v135, s[36:37]
	global_load_dword v187, v135, s[36:37] offset:128
	s_waitcnt vmcnt(32)
	v_add_f32_e32 v188, v120, v188
	v_add_f32_e32 v189, v104, v189
	global_store_dword v136, v188, s[84:85]
	global_store_dword v136, v189, s[84:85] offset:128
	v_add_f32_e32 v190, v121, v190
	v_add_f32_e32 v191, v105, v191
	global_store_dword v137, v190, s[84:85]
	global_store_dword v137, v191, s[84:85] offset:128
	v_add_f32_e32 v192, v122, v192
	v_add_f32_e32 v193, v106, v193
	global_store_dword v138, v192, s[84:85]
	global_store_dword v138, v193, s[84:85] offset:128
	v_add_f32_e32 v194, v123, v194
	v_add_f32_e32 v195, v107, v195
	global_store_dword v139, v194, s[84:85]
	global_store_dword v139, v195, s[84:85] offset:128
	v_add_f32_e32 v196, v124, v196
	v_add_f32_e32 v197, v108, v197
	global_store_dword v140, v196, s[84:85]
	global_store_dword v140, v197, s[84:85] offset:128
	v_add_f32_e32 v198, v125, v198
	v_add_f32_e32 v199, v109, v199
	global_store_dword v141, v198, s[84:85]
	global_store_dword v141, v199, s[84:85] offset:128
	v_add_f32_e32 v200, v126, v200
	v_add_f32_e32 v201, v110, v201
	global_store_dword v142, v200, s[84:85]
	global_store_dword v142, v201, s[84:85] offset:128
	v_add_f32_e32 v202, v127, v202
	v_add_f32_e32 v203, v111, v203
	global_store_dword v143, v202, s[84:85]
	global_store_dword v143, v203, s[84:85] offset:128
	v_add_u32_e32 v136, 0x5000, v135
	global_load_dword v188, v136, s[36:37]
	global_load_dword v189, v136, s[36:37] offset:128
	v_add_u32_e32 v137, 0x1000, v136
	global_load_dword v190, v137, s[36:37]
	global_load_dword v191, v137, s[36:37] offset:128
	v_add_u32_e32 v138, 0x1000, v137
	global_load_dword v192, v138, s[36:37]
	global_load_dword v193, v138, s[36:37] offset:128
	v_add_u32_e32 v139, 0x1000, v138
	global_load_dword v194, v139, s[36:37]
	global_load_dword v195, v139, s[36:37] offset:128
	v_add_u32_e32 v140, 0x5000, v139
	global_load_dword v196, v140, s[36:37]
	global_load_dword v197, v140, s[36:37] offset:128
	v_add_u32_e32 v141, 0x1000, v140
	global_load_dword v198, v141, s[36:37]
	global_load_dword v199, v141, s[36:37] offset:128
	v_add_u32_e32 v142, 0x1000, v141
	global_load_dword v200, v142, s[36:37]
	global_load_dword v201, v142, s[36:37] offset:128
	v_add_u32_e32 v143, 0x1000, v142
	global_load_dword v202, v143, s[36:37]
	global_load_dword v203, v143, s[36:37] offset:128
	s_waitcnt vmcnt(32)
	v_add_f32_e32 v172, v80, v172
	v_add_f32_e32 v173, v64, v173
	global_store_dword v128, v172, s[84:85]
	global_store_dword v128, v173, s[84:85] offset:128
	v_add_f32_e32 v174, v81, v174
	v_add_f32_e32 v175, v65, v175
	global_store_dword v129, v174, s[84:85]
	global_store_dword v129, v175, s[84:85] offset:128
	v_add_f32_e32 v176, v82, v176
	v_add_f32_e32 v177, v66, v177
	global_store_dword v130, v176, s[84:85]
	global_store_dword v130, v177, s[84:85] offset:128
	v_add_f32_e32 v178, v83, v178
	v_add_f32_e32 v179, v67, v179
	global_store_dword v131, v178, s[84:85]
	global_store_dword v131, v179, s[84:85] offset:128
	v_add_f32_e32 v180, v84, v180
	v_add_f32_e32 v181, v68, v181
	global_store_dword v132, v180, s[84:85]
	global_store_dword v132, v181, s[84:85] offset:128
	v_add_f32_e32 v182, v85, v182
	v_add_f32_e32 v183, v69, v183
	global_store_dword v133, v182, s[84:85]
	global_store_dword v133, v183, s[84:85] offset:128
	v_add_f32_e32 v184, v86, v184
	v_add_f32_e32 v185, v70, v185
	global_store_dword v134, v184, s[84:85]
	global_store_dword v134, v185, s[84:85] offset:128
	v_add_f32_e32 v186, v87, v186
	v_add_f32_e32 v187, v71, v187
	global_store_dword v135, v186, s[84:85]
	global_store_dword v135, v187, s[84:85] offset:128
	v_add_u32_e32 v128, 0x5000, v143
	global_load_dword v172, v128, s[36:37]
	global_load_dword v173, v128, s[36:37] offset:128
	v_add_u32_e32 v129, 0x1000, v128
	global_load_dword v174, v129, s[36:37]
	global_load_dword v175, v129, s[36:37] offset:128
	v_add_u32_e32 v130, 0x1000, v129
	global_load_dword v176, v130, s[36:37]
	global_load_dword v177, v130, s[36:37] offset:128
	v_add_u32_e32 v131, 0x1000, v130
	global_load_dword v178, v131, s[36:37]
	global_load_dword v179, v131, s[36:37] offset:128
	v_add_u32_e32 v132, 0x5000, v131
	global_load_dword v180, v132, s[36:37]
	global_load_dword v181, v132, s[36:37] offset:128
	v_add_u32_e32 v133, 0x1000, v132
	global_load_dword v182, v133, s[36:37]
	global_load_dword v183, v133, s[36:37] offset:128
	v_add_u32_e32 v134, 0x1000, v133
	global_load_dword v184, v134, s[36:37]
	global_load_dword v185, v134, s[36:37] offset:128
	v_add_u32_e32 v135, 0x1000, v134
	global_load_dword v186, v135, s[36:37]
	global_load_dword v187, v135, s[36:37] offset:128
	s_waitcnt vmcnt(32)
	v_add_f32_e32 v188, v88, v188
	v_add_f32_e32 v189, v72, v189
	global_store_dword v136, v188, s[84:85]
	global_store_dword v136, v189, s[84:85] offset:128
	v_add_f32_e32 v190, v89, v190
	v_add_f32_e32 v191, v73, v191
	global_store_dword v137, v190, s[84:85]
	global_store_dword v137, v191, s[84:85] offset:128
	v_add_f32_e32 v192, v90, v192
	v_add_f32_e32 v193, v74, v193
	global_store_dword v138, v192, s[84:85]
	global_store_dword v138, v193, s[84:85] offset:128
	v_add_f32_e32 v194, v91, v194
	v_add_f32_e32 v195, v75, v195
	global_store_dword v139, v194, s[84:85]
	global_store_dword v139, v195, s[84:85] offset:128
	v_add_f32_e32 v196, v92, v196
	v_add_f32_e32 v197, v76, v197
	global_store_dword v140, v196, s[84:85]
	global_store_dword v140, v197, s[84:85] offset:128
	v_add_f32_e32 v198, v93, v198
	v_add_f32_e32 v199, v77, v199
	global_store_dword v141, v198, s[84:85]
	global_store_dword v141, v199, s[84:85] offset:128
	v_add_f32_e32 v200, v94, v200
	v_add_f32_e32 v201, v78, v201
	global_store_dword v142, v200, s[84:85]
	global_store_dword v142, v201, s[84:85] offset:128
	v_add_f32_e32 v202, v95, v202
	v_add_f32_e32 v203, v79, v203
	global_store_dword v143, v202, s[84:85]
	global_store_dword v143, v203, s[84:85] offset:128
	v_add_u32_e32 v136, 0x5000, v135
	global_load_dword v188, v136, s[36:37]
	global_load_dword v189, v136, s[36:37] offset:128
	v_add_u32_e32 v137, 0x1000, v136
	global_load_dword v190, v137, s[36:37]
	global_load_dword v191, v137, s[36:37] offset:128
	v_add_u32_e32 v138, 0x1000, v137
	global_load_dword v192, v138, s[36:37]
	global_load_dword v193, v138, s[36:37] offset:128
	v_add_u32_e32 v139, 0x1000, v138
	global_load_dword v194, v139, s[36:37]
	global_load_dword v195, v139, s[36:37] offset:128
	v_add_u32_e32 v140, 0x5000, v139
	global_load_dword v196, v140, s[36:37]
	global_load_dword v197, v140, s[36:37] offset:128
	v_add_u32_e32 v141, 0x1000, v140
	global_load_dword v198, v141, s[36:37]
	global_load_dword v199, v141, s[36:37] offset:128
	v_add_u32_e32 v142, 0x1000, v141
	global_load_dword v200, v142, s[36:37]
	global_load_dword v201, v142, s[36:37] offset:128
	v_add_u32_e32 v143, 0x1000, v142
	global_load_dword v202, v143, s[36:37]
	global_load_dword v203, v143, s[36:37] offset:128
	s_waitcnt vmcnt(32)
	v_add_f32_e32 v172, v48, v172
	v_add_f32_e32 v173, v32, v173
	global_store_dword v128, v172, s[84:85]
	global_store_dword v128, v173, s[84:85] offset:128
	v_add_f32_e32 v174, v49, v174
	v_add_f32_e32 v175, v33, v175
	global_store_dword v129, v174, s[84:85]
	global_store_dword v129, v175, s[84:85] offset:128
	v_add_f32_e32 v176, v50, v176
	v_add_f32_e32 v177, v34, v177
	global_store_dword v130, v176, s[84:85]
	global_store_dword v130, v177, s[84:85] offset:128
	v_add_f32_e32 v178, v51, v178
	v_add_f32_e32 v179, v35, v179
	global_store_dword v131, v178, s[84:85]
	global_store_dword v131, v179, s[84:85] offset:128
	v_add_f32_e32 v180, v52, v180
	v_add_f32_e32 v181, v36, v181
	global_store_dword v132, v180, s[84:85]
	global_store_dword v132, v181, s[84:85] offset:128
	v_add_f32_e32 v182, v53, v182
	v_add_f32_e32 v183, v37, v183
	global_store_dword v133, v182, s[84:85]
	global_store_dword v133, v183, s[84:85] offset:128
	v_add_f32_e32 v184, v54, v184
	v_add_f32_e32 v185, v38, v185
	global_store_dword v134, v184, s[84:85]
	global_store_dword v134, v185, s[84:85] offset:128
	v_add_f32_e32 v186, v55, v186
	v_add_f32_e32 v187, v39, v187
	global_store_dword v135, v186, s[84:85]
	global_store_dword v135, v187, s[84:85] offset:128
	v_add_u32_e32 v128, 0x5000, v143
	global_load_dword v172, v128, s[36:37]
	global_load_dword v173, v128, s[36:37] offset:128
	v_add_u32_e32 v129, 0x1000, v128
	global_load_dword v174, v129, s[36:37]
	global_load_dword v175, v129, s[36:37] offset:128
	v_add_u32_e32 v130, 0x1000, v129
	global_load_dword v176, v130, s[36:37]
	global_load_dword v177, v130, s[36:37] offset:128
	v_add_u32_e32 v131, 0x1000, v130
	global_load_dword v178, v131, s[36:37]
	global_load_dword v179, v131, s[36:37] offset:128
	v_add_u32_e32 v132, 0x5000, v131
	global_load_dword v180, v132, s[36:37]
	global_load_dword v181, v132, s[36:37] offset:128
	v_add_u32_e32 v133, 0x1000, v132
	global_load_dword v182, v133, s[36:37]
	global_load_dword v183, v133, s[36:37] offset:128
	v_add_u32_e32 v134, 0x1000, v133
	global_load_dword v184, v134, s[36:37]
	global_load_dword v185, v134, s[36:37] offset:128
	v_add_u32_e32 v135, 0x1000, v134
	global_load_dword v186, v135, s[36:37]
	global_load_dword v187, v135, s[36:37] offset:128
	s_waitcnt vmcnt(32)
	v_add_f32_e32 v188, v56, v188
	v_add_f32_e32 v189, v40, v189
	global_store_dword v136, v188, s[84:85]
	global_store_dword v136, v189, s[84:85] offset:128
	v_add_f32_e32 v190, v57, v190
	v_add_f32_e32 v191, v41, v191
	global_store_dword v137, v190, s[84:85]
	global_store_dword v137, v191, s[84:85] offset:128
	v_add_f32_e32 v192, v58, v192
	v_add_f32_e32 v193, v42, v193
	global_store_dword v138, v192, s[84:85]
	global_store_dword v138, v193, s[84:85] offset:128
	v_add_f32_e32 v194, v59, v194
	v_add_f32_e32 v195, v43, v195
	global_store_dword v139, v194, s[84:85]
	global_store_dword v139, v195, s[84:85] offset:128
	v_add_f32_e32 v196, v60, v196
	v_add_f32_e32 v197, v44, v197
	global_store_dword v140, v196, s[84:85]
	global_store_dword v140, v197, s[84:85] offset:128
	v_add_f32_e32 v198, v61, v198
	v_add_f32_e32 v199, v45, v199
	global_store_dword v141, v198, s[84:85]
	global_store_dword v141, v199, s[84:85] offset:128
	v_add_f32_e32 v200, v62, v200
	v_add_f32_e32 v201, v46, v201
	global_store_dword v142, v200, s[84:85]
	global_store_dword v142, v201, s[84:85] offset:128
	v_add_f32_e32 v202, v63, v202
	v_add_f32_e32 v203, v47, v203
	global_store_dword v143, v202, s[84:85]
	global_store_dword v143, v203, s[84:85] offset:128
	v_add_u32_e32 v136, 0x5000, v135
	global_load_dword v188, v136, s[36:37]
	global_load_dword v189, v136, s[36:37] offset:128
	v_add_u32_e32 v137, 0x1000, v136
	global_load_dword v190, v137, s[36:37]
	global_load_dword v191, v137, s[36:37] offset:128
	v_add_u32_e32 v138, 0x1000, v137
	global_load_dword v192, v138, s[36:37]
	global_load_dword v193, v138, s[36:37] offset:128
	v_add_u32_e32 v139, 0x1000, v138
	global_load_dword v194, v139, s[36:37]
	global_load_dword v195, v139, s[36:37] offset:128
	v_add_u32_e32 v140, 0x5000, v139
	global_load_dword v196, v140, s[36:37]
	global_load_dword v197, v140, s[36:37] offset:128
	v_add_u32_e32 v141, 0x1000, v140
	global_load_dword v198, v141, s[36:37]
	global_load_dword v199, v141, s[36:37] offset:128
	v_add_u32_e32 v142, 0x1000, v141
	global_load_dword v200, v142, s[36:37]
	global_load_dword v201, v142, s[36:37] offset:128
	v_add_u32_e32 v143, 0x1000, v142
	global_load_dword v202, v143, s[36:37]
	global_load_dword v203, v143, s[36:37] offset:128
	s_waitcnt vmcnt(32)
	v_add_f32_e32 v172, v16, v172
	v_add_f32_e32 v173, v0, v173
	global_store_dword v128, v172, s[84:85]
	global_store_dword v128, v173, s[84:85] offset:128
	v_add_f32_e32 v174, v17, v174
	v_add_f32_e32 v175, v1, v175
	global_store_dword v129, v174, s[84:85]
	global_store_dword v129, v175, s[84:85] offset:128
	v_add_f32_e32 v176, v18, v176
	v_add_f32_e32 v177, v2, v177
	global_store_dword v130, v176, s[84:85]
	global_store_dword v130, v177, s[84:85] offset:128
	v_add_f32_e32 v178, v19, v178
	v_add_f32_e32 v179, v3, v179
	global_store_dword v131, v178, s[84:85]
	global_store_dword v131, v179, s[84:85] offset:128
	v_add_f32_e32 v180, v20, v180
	v_add_f32_e32 v181, v4, v181
	global_store_dword v132, v180, s[84:85]
	global_store_dword v132, v181, s[84:85] offset:128
	v_add_f32_e32 v182, v21, v182
	v_add_f32_e32 v183, v5, v183
	global_store_dword v133, v182, s[84:85]
	global_store_dword v133, v183, s[84:85] offset:128
	v_add_f32_e32 v184, v22, v184
	v_add_f32_e32 v185, v6, v185
	global_store_dword v134, v184, s[84:85]
	global_store_dword v134, v185, s[84:85] offset:128
	v_add_f32_e32 v186, v23, v186
	v_add_f32_e32 v187, v7, v187
	global_store_dword v135, v186, s[84:85]
	global_store_dword v135, v187, s[84:85] offset:128
	s_waitcnt vmcnt(16)
	v_add_f32_e32 v188, v24, v188
	v_add_f32_e32 v189, v8, v189
	global_store_dword v136, v188, s[84:85]
	global_store_dword v136, v189, s[84:85] offset:128
	v_add_f32_e32 v190, v25, v190
	v_add_f32_e32 v191, v9, v191
	global_store_dword v137, v190, s[84:85]
	global_store_dword v137, v191, s[84:85] offset:128
	v_add_f32_e32 v192, v26, v192
	v_add_f32_e32 v193, v10, v193
	global_store_dword v138, v192, s[84:85]
	global_store_dword v138, v193, s[84:85] offset:128
	v_add_f32_e32 v194, v27, v194
	v_add_f32_e32 v195, v11, v195
	global_store_dword v139, v194, s[84:85]
	global_store_dword v139, v195, s[84:85] offset:128
	v_add_f32_e32 v196, v28, v196
	v_add_f32_e32 v197, v12, v197
	global_store_dword v140, v196, s[84:85]
	global_store_dword v140, v197, s[84:85] offset:128
	v_add_f32_e32 v198, v29, v198
	v_add_f32_e32 v199, v13, v199
	global_store_dword v141, v198, s[84:85]
	global_store_dword v141, v199, s[84:85] offset:128
	v_add_f32_e32 v200, v30, v200
	v_add_f32_e32 v201, v14, v201
	global_store_dword v142, v200, s[84:85]
	global_store_dword v142, v201, s[84:85] offset:128
	v_add_f32_e32 v202, v31, v202
	v_add_f32_e32 v203, v15, v203
	global_store_dword v143, v202, s[84:85]
	global_store_dword v143, v203, s[84:85] offset:128
	s_cmpk_lt_i32 s2, 0x100
	s_cbranch_scc1 .LBB0_619
